# v58 + FF1 epilogue: its 12 serialized LDS table reads (4 bias + 8 row scales) issued together behind one wait (row scales into free v240..v253)
# baseline (speedup 1.0000x reference)
; #define PG8_LAS __attribute__((address_space(3)))
; __device__ __forceinline__ unsigned cvt_pk_bf16(float lo, float hi) { unsigned r; asm volatile("v_cvt_pk_bf16_f32 %0, %1, %2" : "=v"(r) : "v"(lo), "v"(hi)); return r; }
; __device__ __forceinline__ f32x4 lds_ld4(const PG8_LAS float* p) { f32x4 v; asm volatile("ds_read_b128 %0, %1\n\ts_waitcnt lgkmcnt(0)" : "=v"(v) : "v"((unsigned)(size_t)p) : "memory"); return v; }
; __device__ __forceinline__ float lds_ld1(const PG8_LAS float* p) { float v; asm volatile("ds_read_b32 %0, %1\n\ts_waitcnt lgkmcnt(0)" : "=v"(v) : "v"((unsigned)(size_t)p) : "memory"); return v; }
;     __device__ __forceinline__ void operator()(const f32x4 (&acc)[2][2][4][2], const Unit& u, int wr, int wc, int fr, int fq) const {
;         const int row0 = u.pm * BM + wr * 64 + fr, cin = wc * 32 + 8 * fq, col0 = u.pn * BM + cin;
;         const PG8_LAS float* bp = cb + (u.pn >> 2) * BM + cin;
;         f32x4 bv[2][2];
; #pragma unroll
;         for (int bj = 0; bj < 2; ++bj)
; #pragma unroll
;             for (int n = 0; n < 2; ++n) bv[bj][n] = lds_ld4(bp + bj * HALF + 4 * n);
; #pragma unroll
;         for (int ai = 0; ai < 2; ++ai)
; #pragma unroll
;             for (int m = 0; m < 4; ++m) { bf16_t* rowp = O + (size_t)(row0 + ai * HALF + m * 16) * ldc + col0; const float r = lds_ld1(rs + ai * HALF + wr * 64 + m * 16 + fr);
; #pragma unroll
;                 for (int bj = 0; bj < 2; ++bj) { f32x4 v0 = acc[ai][bj][m][0] * r + bv[bj][0], v1 = acc[ai][bj][m][1] * r + bv[bj][1];
; #pragma unroll
;                     for (int j = 0; j < 4; ++j) { const float a = fmaxf(v0[j], 0.f), b = fmaxf(v1[j], 0.f); v0[j] = a * a; v1[j] = b * b; }
;                     u32x4 w; w.x = cvt_pk_bf16(v0[0], v0[1]); w.y = cvt_pk_bf16(v0[2], v0[3]); w.z = cvt_pk_bf16(v1[0], v1[1]); w.w = cvt_pk_bf16(v1[2], v1[3]);
;                     *(u32x4*)(rowp + bj * HALF) = w; } }
.LBB0_1254:
	s_lshl_b32 s15, s53, 8
	s_and_b32 s17, s15, 0xfffffc00
	v_add_u32_e32 v130, s17, v168
	ds_read_b128 v[142:145], v130
	v_add_u32_e32 v131, 16, v130
	ds_read_b128 v[138:141], v131
	v_add_u32_e32 v131, 0x200, v130
	ds_read_b128 v[134:137], v131
	v_add_u32_e32 v130, 0x210, v130
	ds_read_b128 v[130:133], v130
	ds_read_b32 v184, v169
	ds_read_b32 v240, v170
	ds_read_b32 v242, v171
	ds_read_b32 v244, v172
	ds_read_b32 v246, v173
	ds_read_b32 v248, v174
	ds_read_b32 v250, v175
	ds_read_b32 v252, v176
	s_waitcnt lgkmcnt(0)
	v_or_b32_e32 v164, s15, v167
	v_pk_fma_f32 v[122:123], v[122:123], v[184:185], v[138:139] op_sel_hi:[1,0,1]
	v_pk_fma_f32 v[126:127], v[126:127], v[184:185], v[142:143] op_sel_hi:[1,0,1]
	v_pk_fma_f32 v[124:125], v[124:125], v[184:185], v[140:141] op_sel_hi:[1,0,1]
	v_max_f32_e32 v122, 0, v122
	v_lshl_add_u32 v180, s22, 8, v1
	v_ashrrev_i32_e32 v165, 31, v164
	v_mov_b64_e32 v[162:163], s[44:45]
	v_pk_fma_f32 v[128:129], v[128:129], v[184:185], v[144:145] op_sel_hi:[1,0,1]
	v_mul_f32_e32 v181, v122, v122
	v_max_f32_e32 v122, 0, v127
	v_max_f32_e32 v123, 0, v123
	v_max_f32_e32 v124, 0, v124
	v_mad_i64_i32 v[182:183], s[36:37], v180, s52, v[162:163]
	v_lshlrev_b64 v[164:165], 1, v[164:165]
	v_max_f32_e32 v126, 0, v126
	v_mul_f32_e32 v122, v122, v122
	v_mul_f32_e32 v127, v123, v123
	v_max_f32_e32 v123, 0, v128
	v_mul_f32_e32 v128, v124, v124
	v_max_f32_e32 v124, 0, v129
	v_max_f32_e32 v125, 0, v125
	v_pk_fma_f32 v[116:117], v[116:117], v[184:185], v[132:133] op_sel_hi:[1,0,1]
	v_pk_fma_f32 v[114:115], v[114:115], v[184:185], v[130:131] op_sel_hi:[1,0,1]
	v_lshl_add_u64 v[182:183], v[182:183], 0, v[164:165]
	v_mul_f32_e32 v126, v126, v126
	v_mul_f32_e32 v123, v123, v123
	v_mul_f32_e32 v124, v124, v124
	v_mul_f32_e32 v125, v125, v125
	v_cvt_pk_bf16_f32 v122, v126, v122
	v_pk_fma_f32 v[120:121], v[120:121], v[184:185], v[136:137] op_sel_hi:[1,0,1]
	v_pk_fma_f32 v[118:119], v[118:119], v[184:185], v[134:135] op_sel_hi:[1,0,1]
	v_max_f32_e32 v114, 0, v114
	v_max_f32_e32 v115, 0, v115
	v_max_f32_e32 v116, 0, v116
	v_cvt_pk_bf16_f32 v123, v123, v124
	v_cvt_pk_bf16_f32 v124, v181, v127
	v_cvt_pk_bf16_f32 v125, v128, v125
	global_store_dwordx4 v[182:183], v[122:125], off
	v_max_f32_e32 v117, 0, v117
	v_max_f32_e32 v118, 0, v118
	v_mul_f32_e32 v122, v114, v114
	v_max_f32_e32 v114, 0, v119
	v_mul_f32_e32 v119, v115, v115
	v_max_f32_e32 v115, 0, v120
	v_mul_f32_e32 v120, v116, v116
	v_max_f32_e32 v116, 0, v121
	v_mul_f32_e32 v114, v114, v114
	v_mul_f32_e32 v115, v115, v115
	v_mul_f32_e32 v116, v116, v116
	v_mul_f32_e32 v117, v117, v117
	v_mul_f32_e32 v118, v118, v118
	v_cvt_pk_bf16_f32 v114, v118, v114
	v_cvt_pk_bf16_f32 v115, v115, v116
	v_cvt_pk_bf16_f32 v116, v122, v119
	v_cvt_pk_bf16_f32 v117, v120, v117
	global_store_dwordx4 v[182:183], v[114:117], off offset:256
	s_andn2_b64 vcc, exec, s[4:5]
	s_mov_b64 s[4:5], -1
	v_or_b32_e32 v114, 16, v180
	v_pk_fma_f32 v[106:107], v[106:107], v[240:241], v[138:139] op_sel_hi:[1,0,1]
	v_pk_fma_f32 v[110:111], v[110:111], v[240:241], v[142:143] op_sel_hi:[1,0,1]
	v_pk_fma_f32 v[108:109], v[108:109], v[240:241], v[140:141] op_sel_hi:[1,0,1]
	v_max_f32_e32 v106, 0, v106
	v_pk_fma_f32 v[112:113], v[112:113], v[240:241], v[144:145] op_sel_hi:[1,0,1]
	v_mul_f32_e32 v117, v106, v106
	v_max_f32_e32 v106, 0, v111
	v_max_f32_e32 v107, 0, v107
	v_max_f32_e32 v108, 0, v108
	v_mad_i64_i32 v[114:115], s[36:37], v114, s52, v[162:163]
	v_max_f32_e32 v110, 0, v110
	v_mul_f32_e32 v106, v106, v106
	v_mul_f32_e32 v111, v107, v107
	v_max_f32_e32 v107, 0, v112
	v_mul_f32_e32 v112, v108, v108
	v_max_f32_e32 v108, 0, v113
	v_max_f32_e32 v109, 0, v109
	v_pk_fma_f32 v[100:101], v[100:101], v[240:241], v[132:133] op_sel_hi:[1,0,1]
	v_pk_fma_f32 v[98:99], v[98:99], v[240:241], v[130:131] op_sel_hi:[1,0,1]
	v_lshl_add_u64 v[114:115], v[114:115], 0, v[164:165]
	v_mul_f32_e32 v110, v110, v110
	v_mul_f32_e32 v107, v107, v107
	v_mul_f32_e32 v108, v108, v108
	v_mul_f32_e32 v109, v109, v109
	v_cvt_pk_bf16_f32 v106, v110, v106
	v_pk_fma_f32 v[104:105], v[104:105], v[240:241], v[136:137] op_sel_hi:[1,0,1]
	v_pk_fma_f32 v[102:103], v[102:103], v[240:241], v[134:135] op_sel_hi:[1,0,1]
	v_max_f32_e32 v98, 0, v98
	v_max_f32_e32 v99, 0, v99
	v_max_f32_e32 v100, 0, v100
	v_cvt_pk_bf16_f32 v107, v107, v108
	v_cvt_pk_bf16_f32 v108, v117, v111
	v_cvt_pk_bf16_f32 v109, v112, v109
	global_store_dwordx4 v[114:115], v[106:109], off
	v_max_f32_e32 v101, 0, v101
	v_max_f32_e32 v102, 0, v102
	v_mul_f32_e32 v106, v98, v98
	v_max_f32_e32 v98, 0, v103
	v_mul_f32_e32 v103, v99, v99
	v_max_f32_e32 v99, 0, v104
	v_mul_f32_e32 v104, v100, v100
	v_max_f32_e32 v100, 0, v105
	v_mul_f32_e32 v98, v98, v98
	v_mul_f32_e32 v99, v99, v99
	v_mul_f32_e32 v100, v100, v100
	v_mul_f32_e32 v101, v101, v101
	v_mul_f32_e32 v102, v102, v102
	v_cvt_pk_bf16_f32 v98, v102, v98
	v_cvt_pk_bf16_f32 v99, v99, v100
	v_cvt_pk_bf16_f32 v100, v106, v103
	v_cvt_pk_bf16_f32 v101, v104, v101
	global_store_dwordx4 v[114:115], v[98:101], off offset:256
	s_nop 1
	v_or_b32_e32 v98, 32, v180
	v_pk_fma_f32 v[90:91], v[90:91], v[242:243], v[138:139] op_sel_hi:[1,0,1]
	v_pk_fma_f32 v[94:95], v[94:95], v[242:243], v[142:143] op_sel_hi:[1,0,1]
	v_pk_fma_f32 v[92:93], v[92:93], v[242:243], v[140:141] op_sel_hi:[1,0,1]
	v_max_f32_e32 v90, 0, v90
	v_pk_fma_f32 v[96:97], v[96:97], v[242:243], v[144:145] op_sel_hi:[1,0,1]
	v_mul_f32_e32 v101, v90, v90
	v_max_f32_e32 v90, 0, v95
	v_max_f32_e32 v91, 0, v91
	v_max_f32_e32 v92, 0, v92
	v_mad_i64_i32 v[98:99], s[36:37], v98, s52, v[162:163]
	v_max_f32_e32 v94, 0, v94
	v_mul_f32_e32 v90, v90, v90
	v_mul_f32_e32 v95, v91, v91
	v_max_f32_e32 v91, 0, v96
; __device__ __forceinline__ unsigned cvt_pk_bf16(float lo, float hi) { unsigned r; asm volatile("v_cvt_pk_bf16_f32 %0, %1, %2" : "=v"(r) : "v"(lo), "v"(hi)); return r; }
; __device__ __forceinline__ float lds_ld1(const PG8_LAS float* p) { float v; asm volatile("ds_read_b32 %0, %1\n\ts_waitcnt lgkmcnt(0)" : "=v"(v) : "v"((unsigned)(size_t)p) : "memory"); return v; }
;     __device__ __forceinline__ void operator()(const f32x4 (&acc)[2][2][4][2], const Unit& u, int wr, int wc, int fr, int fq) const {
;     ...
;             for (int m = 0; m < 4; ++m) { bf16_t* rowp = O + (size_t)(row0 + ai * HALF + m * 16) * ldc + col0; const float r = lds_ld1(rs + ai * HALF + wr * 64 + m * 16 + fr);
; #pragma unroll
;                 for (int bj = 0; bj < 2; ++bj) { f32x4 v0 = acc[ai][bj][m][0] * r + bv[bj][0], v1 = acc[ai][bj][m][1] * r + bv[bj][1];
; #pragma unroll
;                     for (int j = 0; j < 4; ++j) { const float a = fmaxf(v0[j], 0.f), b = fmaxf(v1[j], 0.f); v0[j] = a * a; v1[j] = b * b; }
;                     u32x4 w; w.x = cvt_pk_bf16(v0[0], v0[1]); w.y = cvt_pk_bf16(v0[2], v0[3]); w.z = cvt_pk_bf16(v1[0], v1[1]); w.w = cvt_pk_bf16(v1[2], v1[3]);
;                     *(u32x4*)(rowp + bj * HALF) = w; } }
	v_mul_f32_e32 v96, v92, v92
	v_max_f32_e32 v92, 0, v97
	v_max_f32_e32 v93, 0, v93
	v_pk_fma_f32 v[84:85], v[84:85], v[242:243], v[132:133] op_sel_hi:[1,0,1]
	v_pk_fma_f32 v[82:83], v[82:83], v[242:243], v[130:131] op_sel_hi:[1,0,1]
	v_lshl_add_u64 v[98:99], v[98:99], 0, v[164:165]
	v_mul_f32_e32 v94, v94, v94
	v_mul_f32_e32 v91, v91, v91
	v_mul_f32_e32 v92, v92, v92
	v_mul_f32_e32 v93, v93, v93
	v_cvt_pk_bf16_f32 v90, v94, v90
	v_pk_fma_f32 v[88:89], v[88:89], v[242:243], v[136:137] op_sel_hi:[1,0,1]
	v_pk_fma_f32 v[86:87], v[86:87], v[242:243], v[134:135] op_sel_hi:[1,0,1]
	v_max_f32_e32 v82, 0, v82
	v_max_f32_e32 v83, 0, v83
	v_max_f32_e32 v84, 0, v84
	v_cvt_pk_bf16_f32 v91, v91, v92
	v_cvt_pk_bf16_f32 v92, v101, v95
	v_cvt_pk_bf16_f32 v93, v96, v93
	global_store_dwordx4 v[98:99], v[90:93], off
	v_max_f32_e32 v85, 0, v85
	v_max_f32_e32 v86, 0, v86
	v_mul_f32_e32 v90, v82, v82
	v_max_f32_e32 v82, 0, v87
	v_mul_f32_e32 v87, v83, v83
	v_max_f32_e32 v83, 0, v88
	v_mul_f32_e32 v88, v84, v84
	v_max_f32_e32 v84, 0, v89
	v_mul_f32_e32 v82, v82, v82
	v_mul_f32_e32 v83, v83, v83
	v_mul_f32_e32 v84, v84, v84
	v_mul_f32_e32 v85, v85, v85
	v_mul_f32_e32 v86, v86, v86
	v_cvt_pk_bf16_f32 v82, v86, v82
	v_cvt_pk_bf16_f32 v83, v83, v84
	v_cvt_pk_bf16_f32 v84, v90, v87
	v_cvt_pk_bf16_f32 v85, v88, v85
	global_store_dwordx4 v[98:99], v[82:85], off offset:256
	s_nop 1
	v_or_b32_e32 v82, 48, v180
	v_pk_fma_f32 v[74:75], v[74:75], v[244:245], v[138:139] op_sel_hi:[1,0,1]
	v_pk_fma_f32 v[78:79], v[78:79], v[244:245], v[142:143] op_sel_hi:[1,0,1]
	v_pk_fma_f32 v[76:77], v[76:77], v[244:245], v[140:141] op_sel_hi:[1,0,1]
	v_max_f32_e32 v74, 0, v74
	v_pk_fma_f32 v[80:81], v[80:81], v[244:245], v[144:145] op_sel_hi:[1,0,1]
	v_mul_f32_e32 v85, v74, v74
	v_max_f32_e32 v74, 0, v79
	v_max_f32_e32 v75, 0, v75
	v_max_f32_e32 v76, 0, v76
	v_mad_i64_i32 v[82:83], s[36:37], v82, s52, v[162:163]
	v_max_f32_e32 v78, 0, v78
	v_mul_f32_e32 v74, v74, v74
	v_mul_f32_e32 v79, v75, v75
	v_max_f32_e32 v75, 0, v80
	v_mul_f32_e32 v80, v76, v76
	v_max_f32_e32 v76, 0, v81
	v_max_f32_e32 v77, 0, v77
	v_pk_fma_f32 v[68:69], v[68:69], v[244:245], v[132:133] op_sel_hi:[1,0,1]
	v_pk_fma_f32 v[66:67], v[66:67], v[244:245], v[130:131] op_sel_hi:[1,0,1]
	v_lshl_add_u64 v[82:83], v[82:83], 0, v[164:165]
	v_mul_f32_e32 v78, v78, v78
	v_mul_f32_e32 v75, v75, v75
	v_mul_f32_e32 v76, v76, v76
	v_mul_f32_e32 v77, v77, v77
	v_cvt_pk_bf16_f32 v74, v78, v74
	v_pk_fma_f32 v[72:73], v[72:73], v[244:245], v[136:137] op_sel_hi:[1,0,1]
	v_pk_fma_f32 v[70:71], v[70:71], v[244:245], v[134:135] op_sel_hi:[1,0,1]
	v_max_f32_e32 v66, 0, v66
	v_max_f32_e32 v67, 0, v67
	v_max_f32_e32 v68, 0, v68
	v_cvt_pk_bf16_f32 v75, v75, v76
	v_cvt_pk_bf16_f32 v76, v85, v79
	v_cvt_pk_bf16_f32 v77, v80, v77
	global_store_dwordx4 v[82:83], v[74:77], off
	v_max_f32_e32 v69, 0, v69
	v_max_f32_e32 v70, 0, v70
	v_mul_f32_e32 v74, v66, v66
	v_max_f32_e32 v66, 0, v71
	v_mul_f32_e32 v71, v67, v67
	v_max_f32_e32 v67, 0, v72
	v_mul_f32_e32 v72, v68, v68
	v_max_f32_e32 v68, 0, v73
	v_mul_f32_e32 v66, v66, v66
	v_mul_f32_e32 v67, v67, v67
	v_mul_f32_e32 v68, v68, v68
	v_mul_f32_e32 v69, v69, v69
	v_mul_f32_e32 v70, v70, v70
	v_cvt_pk_bf16_f32 v66, v70, v66
	v_cvt_pk_bf16_f32 v67, v67, v68
	v_cvt_pk_bf16_f32 v68, v74, v71
	v_cvt_pk_bf16_f32 v69, v72, v69
	global_store_dwordx4 v[82:83], v[66:69], off offset:256
	s_nop 1
	v_add_u32_e32 v66, 0x80, v180
	v_pk_fma_f32 v[58:59], v[58:59], v[246:247], v[138:139] op_sel_hi:[1,0,1]
	v_pk_fma_f32 v[62:63], v[62:63], v[246:247], v[142:143] op_sel_hi:[1,0,1]
	v_pk_fma_f32 v[60:61], v[60:61], v[246:247], v[140:141] op_sel_hi:[1,0,1]
	v_max_f32_e32 v58, 0, v58
	v_pk_fma_f32 v[64:65], v[64:65], v[246:247], v[144:145] op_sel_hi:[1,0,1]
	v_mul_f32_e32 v69, v58, v58
	v_max_f32_e32 v58, 0, v63
	v_max_f32_e32 v59, 0, v59
	v_max_f32_e32 v60, 0, v60
	v_mad_i64_i32 v[66:67], s[36:37], v66, s52, v[162:163]
	v_max_f32_e32 v62, 0, v62
	v_mul_f32_e32 v58, v58, v58
	v_mul_f32_e32 v63, v59, v59
	v_max_f32_e32 v59, 0, v64
	v_mul_f32_e32 v64, v60, v60
	v_max_f32_e32 v60, 0, v65
	v_max_f32_e32 v61, 0, v61
	v_pk_fma_f32 v[52:53], v[52:53], v[246:247], v[132:133] op_sel_hi:[1,0,1]
	v_pk_fma_f32 v[50:51], v[50:51], v[246:247], v[130:131] op_sel_hi:[1,0,1]
	v_lshl_add_u64 v[66:67], v[66:67], 0, v[164:165]
	v_mul_f32_e32 v62, v62, v62
	v_mul_f32_e32 v59, v59, v59
	v_mul_f32_e32 v60, v60, v60
	v_mul_f32_e32 v61, v61, v61
	v_cvt_pk_bf16_f32 v58, v62, v58
	v_pk_fma_f32 v[56:57], v[56:57], v[246:247], v[136:137] op_sel_hi:[1,0,1]
	v_pk_fma_f32 v[54:55], v[54:55], v[246:247], v[134:135] op_sel_hi:[1,0,1]
	v_max_f32_e32 v50, 0, v50
	v_max_f32_e32 v51, 0, v51
	v_max_f32_e32 v52, 0, v52
	v_cvt_pk_bf16_f32 v59, v59, v60
	v_cvt_pk_bf16_f32 v60, v69, v63
	v_cvt_pk_bf16_f32 v61, v64, v61
	global_store_dwordx4 v[66:67], v[58:61], off
	v_max_f32_e32 v53, 0, v53
	v_max_f32_e32 v54, 0, v54
	v_mul_f32_e32 v58, v50, v50
	v_max_f32_e32 v50, 0, v55
	v_mul_f32_e32 v55, v51, v51
	v_max_f32_e32 v51, 0, v56
	v_mul_f32_e32 v56, v52, v52
	v_max_f32_e32 v52, 0, v57
	v_mul_f32_e32 v50, v50, v50
	v_mul_f32_e32 v51, v51, v51
	v_mul_f32_e32 v52, v52, v52
	v_mul_f32_e32 v53, v53, v53
	v_mul_f32_e32 v54, v54, v54
	v_cvt_pk_bf16_f32 v50, v54, v50
	v_cvt_pk_bf16_f32 v51, v51, v52
	v_cvt_pk_bf16_f32 v52, v58, v55
	v_cvt_pk_bf16_f32 v53, v56, v53
	global_store_dwordx4 v[66:67], v[50:53], off offset:256
	s_nop 1
	v_add_u32_e32 v50, 0x90, v180
	v_pk_fma_f32 v[42:43], v[42:43], v[248:249], v[138:139] op_sel_hi:[1,0,1]
	v_pk_fma_f32 v[46:47], v[46:47], v[248:249], v[142:143] op_sel_hi:[1,0,1]
	v_pk_fma_f32 v[44:45], v[44:45], v[248:249], v[140:141] op_sel_hi:[1,0,1]
; __device__ __forceinline__ unsigned cvt_pk_bf16(float lo, float hi) { unsigned r; asm volatile("v_cvt_pk_bf16_f32 %0, %1, %2" : "=v"(r) : "v"(lo), "v"(hi)); return r; }
; __device__ __forceinline__ float lds_ld1(const PG8_LAS float* p) { float v; asm volatile("ds_read_b32 %0, %1\n\ts_waitcnt lgkmcnt(0)" : "=v"(v) : "v"((unsigned)(size_t)p) : "memory"); return v; }
;     __device__ __forceinline__ void operator()(const f32x4 (&acc)[2][2][4][2], const Unit& u, int wr, int wc, int fr, int fq) const {
;     ...
;             for (int m = 0; m < 4; ++m) { bf16_t* rowp = O + (size_t)(row0 + ai * HALF + m * 16) * ldc + col0; const float r = lds_ld1(rs + ai * HALF + wr * 64 + m * 16 + fr);
; #pragma unroll
;                 for (int bj = 0; bj < 2; ++bj) { f32x4 v0 = acc[ai][bj][m][0] * r + bv[bj][0], v1 = acc[ai][bj][m][1] * r + bv[bj][1];
; #pragma unroll
;                     for (int j = 0; j < 4; ++j) { const float a = fmaxf(v0[j], 0.f), b = fmaxf(v1[j], 0.f); v0[j] = a * a; v1[j] = b * b; }
;                     u32x4 w; w.x = cvt_pk_bf16(v0[0], v0[1]); w.y = cvt_pk_bf16(v0[2], v0[3]); w.z = cvt_pk_bf16(v1[0], v1[1]); w.w = cvt_pk_bf16(v1[2], v1[3]);
;                     *(u32x4*)(rowp + bj * HALF) = w; } }
	v_max_f32_e32 v42, 0, v42
	v_pk_fma_f32 v[48:49], v[48:49], v[248:249], v[144:145] op_sel_hi:[1,0,1]
	v_mul_f32_e32 v53, v42, v42
	v_max_f32_e32 v42, 0, v47
	v_max_f32_e32 v43, 0, v43
	v_max_f32_e32 v44, 0, v44
	v_mad_i64_i32 v[50:51], s[36:37], v50, s52, v[162:163]
	v_max_f32_e32 v46, 0, v46
	v_mul_f32_e32 v42, v42, v42
	v_mul_f32_e32 v47, v43, v43
	v_max_f32_e32 v43, 0, v48
	v_mul_f32_e32 v48, v44, v44
	v_max_f32_e32 v44, 0, v49
	v_max_f32_e32 v45, 0, v45
	v_pk_fma_f32 v[36:37], v[36:37], v[248:249], v[132:133] op_sel_hi:[1,0,1]
	v_pk_fma_f32 v[34:35], v[34:35], v[248:249], v[130:131] op_sel_hi:[1,0,1]
	v_lshl_add_u64 v[50:51], v[50:51], 0, v[164:165]
	v_mul_f32_e32 v46, v46, v46
	v_mul_f32_e32 v43, v43, v43
	v_mul_f32_e32 v44, v44, v44
	v_mul_f32_e32 v45, v45, v45
	v_cvt_pk_bf16_f32 v42, v46, v42
	v_pk_fma_f32 v[40:41], v[40:41], v[248:249], v[136:137] op_sel_hi:[1,0,1]
	v_pk_fma_f32 v[38:39], v[38:39], v[248:249], v[134:135] op_sel_hi:[1,0,1]
	v_max_f32_e32 v34, 0, v34
	v_max_f32_e32 v35, 0, v35
	v_max_f32_e32 v36, 0, v36
	v_cvt_pk_bf16_f32 v43, v43, v44
	v_cvt_pk_bf16_f32 v44, v53, v47
	v_cvt_pk_bf16_f32 v45, v48, v45
	global_store_dwordx4 v[50:51], v[42:45], off
	v_max_f32_e32 v37, 0, v37
	v_max_f32_e32 v38, 0, v38
	v_mul_f32_e32 v42, v34, v34
	v_max_f32_e32 v34, 0, v39
	v_mul_f32_e32 v39, v35, v35
	v_max_f32_e32 v35, 0, v40
	v_mul_f32_e32 v40, v36, v36
	v_max_f32_e32 v36, 0, v41
	v_mul_f32_e32 v34, v34, v34
	v_mul_f32_e32 v35, v35, v35
	v_mul_f32_e32 v36, v36, v36
	v_mul_f32_e32 v37, v37, v37
	v_mul_f32_e32 v38, v38, v38
	v_cvt_pk_bf16_f32 v34, v38, v34
	v_cvt_pk_bf16_f32 v35, v35, v36
	v_cvt_pk_bf16_f32 v36, v42, v39
	v_cvt_pk_bf16_f32 v37, v40, v37
	global_store_dwordx4 v[50:51], v[34:37], off offset:256
	s_nop 1
	v_add_u32_e32 v34, 0xa0, v180
	v_pk_fma_f32 v[26:27], v[26:27], v[250:251], v[138:139] op_sel_hi:[1,0,1]
	v_pk_fma_f32 v[30:31], v[30:31], v[250:251], v[142:143] op_sel_hi:[1,0,1]
	v_pk_fma_f32 v[28:29], v[28:29], v[250:251], v[140:141] op_sel_hi:[1,0,1]
	v_max_f32_e32 v26, 0, v26
	v_pk_fma_f32 v[32:33], v[32:33], v[250:251], v[144:145] op_sel_hi:[1,0,1]
	v_mul_f32_e32 v37, v26, v26
	v_max_f32_e32 v26, 0, v31
	v_max_f32_e32 v27, 0, v27
	v_max_f32_e32 v28, 0, v28
	v_mad_i64_i32 v[34:35], s[36:37], v34, s52, v[162:163]
	v_max_f32_e32 v30, 0, v30
	v_mul_f32_e32 v26, v26, v26
	v_mul_f32_e32 v31, v27, v27
	v_max_f32_e32 v27, 0, v32
	v_mul_f32_e32 v32, v28, v28
	v_max_f32_e32 v28, 0, v33
	v_max_f32_e32 v29, 0, v29
	v_pk_fma_f32 v[20:21], v[20:21], v[250:251], v[132:133] op_sel_hi:[1,0,1]
	v_pk_fma_f32 v[18:19], v[18:19], v[250:251], v[130:131] op_sel_hi:[1,0,1]
	v_lshl_add_u64 v[34:35], v[34:35], 0, v[164:165]
	v_mul_f32_e32 v30, v30, v30
	v_mul_f32_e32 v27, v27, v27
	v_mul_f32_e32 v28, v28, v28
	v_mul_f32_e32 v29, v29, v29
	v_cvt_pk_bf16_f32 v26, v30, v26
	v_pk_fma_f32 v[24:25], v[24:25], v[250:251], v[136:137] op_sel_hi:[1,0,1]
	v_pk_fma_f32 v[22:23], v[22:23], v[250:251], v[134:135] op_sel_hi:[1,0,1]
	v_max_f32_e32 v18, 0, v18
	v_max_f32_e32 v19, 0, v19
	v_max_f32_e32 v20, 0, v20
	v_cvt_pk_bf16_f32 v27, v27, v28
	v_cvt_pk_bf16_f32 v28, v37, v31
	v_cvt_pk_bf16_f32 v29, v32, v29
	global_store_dwordx4 v[34:35], v[26:29], off
	v_max_f32_e32 v21, 0, v21
	v_max_f32_e32 v22, 0, v22
	v_mul_f32_e32 v26, v18, v18
	v_max_f32_e32 v18, 0, v23
	v_mul_f32_e32 v23, v19, v19
	v_max_f32_e32 v19, 0, v24
	v_mul_f32_e32 v24, v20, v20
	v_max_f32_e32 v20, 0, v25
	v_mul_f32_e32 v18, v18, v18
	v_mul_f32_e32 v19, v19, v19
	v_mul_f32_e32 v20, v20, v20
	v_mul_f32_e32 v21, v21, v21
	v_mul_f32_e32 v22, v22, v22
	v_cvt_pk_bf16_f32 v18, v22, v18
	v_cvt_pk_bf16_f32 v19, v19, v20
	v_cvt_pk_bf16_f32 v20, v26, v23
	v_cvt_pk_bf16_f32 v21, v24, v21
	global_store_dwordx4 v[34:35], v[18:21], off offset:256
	s_nop 1
	v_add_u32_e32 v18, 0xb0, v180
	v_pk_fma_f32 v[10:11], v[10:11], v[252:253], v[138:139] op_sel_hi:[1,0,1]
	v_pk_fma_f32 v[14:15], v[14:15], v[252:253], v[142:143] op_sel_hi:[1,0,1]
	v_pk_fma_f32 v[12:13], v[12:13], v[252:253], v[140:141] op_sel_hi:[1,0,1]
	v_max_f32_e32 v10, 0, v10
	v_pk_fma_f32 v[16:17], v[16:17], v[252:253], v[144:145] op_sel_hi:[1,0,1]
	v_mul_f32_e32 v21, v10, v10
	v_max_f32_e32 v10, 0, v15
	v_max_f32_e32 v11, 0, v11
	v_max_f32_e32 v12, 0, v12
	v_mad_i64_i32 v[18:19], s[36:37], v18, s52, v[162:163]
	v_max_f32_e32 v14, 0, v14
	v_mul_f32_e32 v10, v10, v10
	v_mul_f32_e32 v15, v11, v11
	v_max_f32_e32 v11, 0, v16
	v_mul_f32_e32 v16, v12, v12
	v_max_f32_e32 v12, 0, v17
	v_max_f32_e32 v13, 0, v13
	v_pk_fma_f32 v[4:5], v[4:5], v[252:253], v[132:133] op_sel_hi:[1,0,1]
	v_pk_fma_f32 v[2:3], v[2:3], v[252:253], v[130:131] op_sel_hi:[1,0,1]
	v_lshl_add_u64 v[18:19], v[18:19], 0, v[164:165]
	v_mul_f32_e32 v14, v14, v14
	v_mul_f32_e32 v11, v11, v11
	v_mul_f32_e32 v12, v12, v12
	v_mul_f32_e32 v13, v13, v13
	v_cvt_pk_bf16_f32 v10, v14, v10
	v_pk_fma_f32 v[8:9], v[8:9], v[252:253], v[136:137] op_sel_hi:[1,0,1]
	v_pk_fma_f32 v[6:7], v[6:7], v[252:253], v[134:135] op_sel_hi:[1,0,1]
	v_max_f32_e32 v2, 0, v2
	v_max_f32_e32 v3, 0, v3
	v_max_f32_e32 v4, 0, v4
	v_cvt_pk_bf16_f32 v11, v11, v12
	v_cvt_pk_bf16_f32 v12, v21, v15
	v_cvt_pk_bf16_f32 v13, v16, v13
	global_store_dwordx4 v[18:19], v[10:13], off
	v_max_f32_e32 v5, 0, v5
	v_max_f32_e32 v6, 0, v6
	v_mul_f32_e32 v10, v2, v2
	v_max_f32_e32 v2, 0, v7
	v_mul_f32_e32 v7, v3, v3
	v_max_f32_e32 v3, 0, v8
	v_mul_f32_e32 v8, v4, v4
	v_max_f32_e32 v4, 0, v9
	v_mul_f32_e32 v2, v2, v2
	v_mul_f32_e32 v3, v3, v3
	v_mul_f32_e32 v4, v4, v4
	v_mul_f32_e32 v5, v5, v5
	v_mul_f32_e32 v6, v6, v6
	v_cvt_pk_bf16_f32 v2, v6, v2
	v_cvt_pk_bf16_f32 v3, v3, v4
	v_cvt_pk_bf16_f32 v4, v10, v7
	v_cvt_pk_bf16_f32 v5, v8, v5
	global_store_dwordx4 v[18:19], v[2:5], off offset:256
	s_cbranch_vccnz .LBB0_1243
	s_andn2_b64 vcc, exec, s[6:7]
	s_cbranch_vccnz .LBB0_1242
	s_branch .LBB0_1242
